# MLA loop: one static s_setprio 1 for the older wave half (waves 0-3) at loop entry, reset at loop exit
# speedup vs baseline: 1.0011x; 1.0011x over previous
; __device__ __forceinline__ void mla_unit(LAS unsigned char* lds, const bf16_t* Q, const bf16_t* K, const bf16_t* V, bf16_t* Y, const float* qgain, const float* ROPE, int b, int h, int qb) {
;     ...
;     if (wid >= 4) __builtin_amdgcn_s_setprio(1);
;     for (int t = 0; t < 64; t += 2) { MLA_STEP(p0, p1, n0, n1, t, ka1, kb1, vv0, ka0, kb0, vv1); MLA_STEP(n0, n1, p0, p1, t + 1, ka0, kb0, vv1, ka1, kb1, vv0); }
;     __builtin_amdgcn_s_setprio(0);
.Lmla_glue_L:
	global_load_dwordx4 v[106:109], v212, s[2:3]
	global_load_dwordx4 v[110:113], v214, s[2:3]
	global_load_dwordx4 v[102:105], v210, s[6:7]
	v_add_u32_e32 v212, 0x3000, v212
	v_add_u32_e32 v214, 0x3000, v214
	v_add_u32_e32 v210, 0x2000, v210
	s_setprio 1
	s_branch .Lmla_loop_L
